# v23 + remaining dword stores write-through; L2 writeback dropped from the XCD grid-barrier leader path (write-through payload + drained flag form)
# speedup vs baseline: 1.0134x; 1.0021x over previous
; __device__ __forceinline__ void prologue(const Args& a, LAS unsigned char* lds) {
;     ...
;         const int q = ((int)kq) & 3;
;         const double c = (q == 0) ? cn : (q == 1) ? -sn : (q == 2) ? -cn : sn;
;         const double s = (q == 0) ? sn : (q == 1) ? cn : (q == 2) ? -sn : -cn;
;         cs[pos * 32 + i] = (float)c; cs[pos * 32 + 16 + i] = (float)s;
;     }
.LBB0_49:
	s_or_b64 exec, exec, s[30:31]
	v_cmp_eq_u32_e64 s[4:5], 2, v30
	v_add_u32_e32 v1, s36, v1
	v_cvt_f32_f64_e32 v26, v[26:27]
	v_cndmask_b32_e64 v31, v24, v22, s[4:5]
	v_cndmask_b32_e64 v32, -v25, -v23, s[4:5]
	v_cmp_eq_u32_e64 s[4:5], 1, v30
	s_nop 1
	v_cndmask_b32_e64 v24, v31, v24, s[4:5]
	v_cndmask_b32_e64 v25, v32, v25, s[4:5]
	v_cndmask_b32_e64 v22, v24, v22, s[0:1]
	v_lshl_or_b32 v24, v29, 5, v28
	v_cndmask_b32_e64 v23, v25, v23, s[0:1]
	v_ashrrev_i32_e32 v25, 31, v24
	v_cmp_lt_i32_e64 s[0:1], s37, v1
	v_lshl_add_u64 v[24:25], v[24:25], 2, s[6:7]
	v_cvt_f32_f64_e32 v22, v[22:23]
	s_or_b64 s[14:15], s[0:1], s[14:15]
	global_store_dword v[24:25], v26, off sc0 sc1
	global_store_dword v[24:25], v22, off offset:64 sc0 sc1
	s_andn2_b64 exec, exec, s[14:15]
	s_cbranch_execz .LBB0_57

; __global__ void __launch_bounds__(512, 2) mega_fwd(Args a) {
;     ...
;         if (blockIdx.x == 0) { unsigned* bw = (unsigned*)(a.ws + W_BAR); for (int i = threadIdx.x; i < XCD_BAR_WORDS; i += 512) bw[i] = 0u; }
.LBB0_61:
	s_mov_b32 s7, s6
	s_or_b64 s[0:1], s[6:7], s[2:3]
	v_cmp_le_u32_e32 vcc, s1, v1
	v_cmp_le_u32_e64 s[0:1], s0, v2
	s_waitcnt lgkmcnt(0)
	s_and_saveexec_b64 s[14:15], s[0:1]
	s_cbranch_execz .LBB0_63
	v_mov_b32_e32 v4, v6
	v_lshl_add_u64 v[8:9], v[4:5], 2, s[38:39]
	global_store_dword v[8:9], v5, off sc0 sc1
.LBB0_63:
	s_or_b64 exec, exec, s[14:15]
	s_and_saveexec_b64 s[0:1], vcc
	s_cbranch_execz .LBB0_60
	v_mov_b32_e32 v4, v7
	v_lshl_add_u64 v[8:9], v[4:5], 2, s[38:39]
	global_store_dword v[8:9], v5, off sc0 sc1
	s_branch .LBB0_60

; __device__ __forceinline__ unsigned xb_add(unsigned* p, unsigned v) { return __hip_atomic_fetch_add(p, v, __ATOMIC_RELAXED, __HIP_MEMORY_SCOPE_AGENT); }
; __device__ __forceinline__ void xcd_barrier(const XcdBarrier& b) {
;     ...
;         const unsigned old = xb_add(&bar[XB_XSUB(b.x)], 1u);
;         const unsigned gen = old / nloc;
;         if (old + 1u == (gen + 1u) * nloc) {
;             __builtin_amdgcn_fence(__ATOMIC_RELEASE, "agent");
;             asm volatile("s_waitcnt vmcnt(0)" ::: "memory");
;             const unsigned og = xb_add(&bar[XB_TOP], 1u);
.LBB0_147:
	s_andn2_saveexec_b64 s[2:3], s[6:7]
	s_cbranch_execz .LBB0_165
	s_mov_b64 s[6:7], exec
	s_waitcnt lgkmcnt(0)
	s_waitcnt vmcnt(0)
	v_mbcnt_lo_u32_b32 v1, s6, 0
	v_mbcnt_hi_u32_b32 v1, s7, v1
	v_cmp_eq_u32_e32 vcc, 0, v1
	s_and_saveexec_b64 s[8:9], vcc
	s_cbranch_execz .LBB0_150
	s_bcnt1_i32_b64 s2, s[6:7]
	v_mov_b32_e32 v2, s2
	v_readlane_b32 s2, v254, 37
	v_readlane_b32 s3, v254, 38
	s_nop 4
	global_atomic_add v2, v179, v2, s[2:3] sc0

; __device__ __forceinline__ unsigned cvtpk(float lo, float hi) { f32x2_t v = {lo, hi}; bf16x2_t b = __builtin_convertvector(v, bf16x2_t); return __builtin_bit_cast(unsigned, b); }
; __device__ __forceinline__ void mla_prep_phase(const bf16_t* projb, const float* gq, const float* gkv, const float* cs, bf16_t* cqn, bf16_t* ckvn, bf16_t* krope, int rows) {
;     ...
;             if (lane < 16) { u32x4 ob; ob.x = cvtpk(xb[0] * rkv * gB0[0], xb[1] * rkv * gB0[1]); ob.y = cvtpk(xb[2] * rkv * gB0[2], xb[3] * rkv * gB0[3]);
;                 ob.z = cvtpk(xb[4] * rkv * gB1[0], xb[5] * rkv * gB1[1]); ob.w = cvtpk(xb[6] * rkv * gB1[2], xb[7] * rkv * gB1[3]);
;                 *(u32x4*)(ckvn + (size_t)m * 256 + 8 * (16 + lane)) = ob;
;                 const float x1 = bf1(r1[r]), x2 = bf1(r2[r]);
;                 *(unsigned*)(krope + (size_t)m * 32 + 2 * lane) = cvtpk(x1 * cc[r] - x2 * sn[r], x1 * sn[r] + x2 * cc[r]); } }
.LBB0_220:
	v_pk_mul_f32 v[42:43], v[88:89], v[84:85] op_sel_hi:[0,1]
	v_pk_mul_f32 v[42:43], v[0:1], v[42:43]
	s_nop 0
	v_cvt_pk_bf16_f32 v84, v42, v43
	v_pk_mul_f32 v[42:43], v[88:89], v[82:83] op_sel_hi:[0,1]
	v_pk_mul_f32 v[42:43], v[2:3], v[42:43]
	s_nop 0
	v_cvt_pk_bf16_f32 v85, v42, v43
	v_pk_mul_f32 v[42:43], v[88:89], v[80:81] op_sel_hi:[0,1]
	v_pk_mul_f32 v[42:43], v[4:5], v[42:43]
	s_nop 0
	v_cvt_pk_bf16_f32 v86, v42, v43
	v_pk_mul_f32 v[42:43], v[88:89], v[78:79] op_sel_hi:[0,1]
	v_pk_mul_f32 v[42:43], v[6:7], v[42:43]
	s_nop 0
	v_cvt_pk_bf16_f32 v87, v42, v43
	s_waitcnt vmcnt(20)
	v_lshlrev_b32_e32 v43, 16, v77
	v_lshlrev_b32_e32 v42, 16, v75
	s_waitcnt vmcnt(18)
	v_pk_mul_f32 v[76:77], v[76:77], v[42:43] op_sel:[0,1] op_sel_hi:[0,0]
	v_pk_fma_f32 v[78:79], v[74:75], v[42:43], v[76:77] neg_lo:[0,0,1] neg_hi:[0,0,1]
	v_pk_fma_f32 v[42:43], v[74:75], v[42:43], v[76:77] op_sel_hi:[0,1,1]
	v_cvt_pk_bf16_f32 v42, v78, v43
	global_store_dwordx4 v[44:45], v[84:87], off offset:-512 sc0 sc1
	global_store_dword v[40:41], v42, off offset:-128 sc0 sc1

; __device__ __forceinline__ unsigned cvtpk(float lo, float hi) { f32x2_t v = {lo, hi}; bf16x2_t b = __builtin_convertvector(v, bf16x2_t); return __builtin_bit_cast(unsigned, b); }
; __device__ __forceinline__ void mla_prep_phase(const bf16_t* projb, const float* gq, const float* gkv, const float* cs, bf16_t* cqn, bf16_t* ckvn, bf16_t* krope, int rows) {
;     ...
;             if (lane < 16) { u32x4 ob; ob.x = cvtpk(xb[0] * rkv * gB0[0], xb[1] * rkv * gB0[1]); ob.y = cvtpk(xb[2] * rkv * gB0[2], xb[3] * rkv * gB0[3]);
;                 ob.z = cvtpk(xb[4] * rkv * gB1[0], xb[5] * rkv * gB1[1]); ob.w = cvtpk(xb[6] * rkv * gB1[2], xb[7] * rkv * gB1[3]);
;                 *(u32x4*)(ckvn + (size_t)m * 256 + 8 * (16 + lane)) = ob;
;                 const float x1 = bf1(r1[r]), x2 = bf1(r2[r]);
;                 *(unsigned*)(krope + (size_t)m * 32 + 2 * lane) = cvtpk(x1 * cc[r] - x2 * sn[r], x1 * sn[r] + x2 * cc[r]); } }
.LBB0_224:
	v_pk_mul_f32 v[32:33], v[84:85], v[42:43] op_sel_hi:[0,1]
	v_pk_mul_f32 v[34:35], v[84:85], v[36:37] op_sel_hi:[0,1]
	v_pk_mul_f32 v[32:33], v[0:1], v[32:33]
	v_pk_mul_f32 v[34:35], v[2:3], v[34:35]
	v_cvt_pk_bf16_f32 v32, v32, v33
	v_cvt_pk_bf16_f32 v33, v34, v35
	v_pk_mul_f32 v[34:35], v[84:85], v[74:75] op_sel_hi:[0,1]
	v_pk_mul_f32 v[36:37], v[84:85], v[38:39] op_sel_hi:[0,1]
	v_pk_mul_f32 v[34:35], v[4:5], v[34:35]
	v_pk_mul_f32 v[36:37], v[6:7], v[36:37]
	v_cvt_pk_bf16_f32 v34, v34, v35
	v_cvt_pk_bf16_f32 v35, v36, v37
	global_store_dwordx4 v[44:45], v[32:35], off sc0 sc1
	s_waitcnt vmcnt(15)
	s_nop 0
	v_lshlrev_b32_e32 v33, 16, v95
	v_lshlrev_b32_e32 v32, 16, v71
	s_waitcnt vmcnt(13)
	v_pk_mul_f32 v[34:35], v[72:73], v[32:33] op_sel:[0,1] op_sel_hi:[0,0]
	v_pk_fma_f32 v[36:37], v[70:71], v[32:33], v[34:35] neg_lo:[0,0,1] neg_hi:[0,0,1]
	v_pk_fma_f32 v[32:33], v[70:71], v[32:33], v[34:35] op_sel_hi:[0,1,1]
	v_cvt_pk_bf16_f32 v32, v36, v33
	global_store_dword v[40:41], v32, off offset:-64 sc0 sc1

; __device__ __forceinline__ unsigned cvtpk(float lo, float hi) { f32x2_t v = {lo, hi}; bf16x2_t b = __builtin_convertvector(v, bf16x2_t); return __builtin_bit_cast(unsigned, b); }
; __device__ __forceinline__ void mla_prep_phase(const bf16_t* projb, const float* gq, const float* gkv, const float* cs, bf16_t* cqn, bf16_t* ckvn, bf16_t* krope, int rows) {
;     ...
;             if (lane < 16) { u32x4 ob; ob.x = cvtpk(xb[0] * rkv * gB0[0], xb[1] * rkv * gB0[1]); ob.y = cvtpk(xb[2] * rkv * gB0[2], xb[3] * rkv * gB0[3]);
;                 ob.z = cvtpk(xb[4] * rkv * gB1[0], xb[5] * rkv * gB1[1]); ob.w = cvtpk(xb[6] * rkv * gB1[2], xb[7] * rkv * gB1[3]);
;                 *(u32x4*)(ckvn + (size_t)m * 256 + 8 * (16 + lane)) = ob;
;                 const float x1 = bf1(r1[r]), x2 = bf1(r2[r]);
;                 *(unsigned*)(krope + (size_t)m * 32 + 2 * lane) = cvtpk(x1 * cc[r] - x2 * sn[r], x1 * sn[r] + x2 * cc[r]); } }
.LBB0_228:
	v_pk_mul_f32 v[24:25], v[72:73], v[32:33] op_sel_hi:[0,1]
	v_pk_mul_f32 v[26:27], v[72:73], v[28:29] op_sel_hi:[0,1]
	v_pk_mul_f32 v[24:25], v[0:1], v[24:25]
	v_pk_mul_f32 v[26:27], v[2:3], v[26:27]
	v_cvt_pk_bf16_f32 v24, v24, v25
	v_cvt_pk_bf16_f32 v25, v26, v27
	v_pk_mul_f32 v[26:27], v[72:73], v[34:35] op_sel_hi:[0,1]
	v_pk_mul_f32 v[28:29], v[72:73], v[30:31] op_sel_hi:[0,1]
	v_pk_mul_f32 v[26:27], v[4:5], v[26:27]
	v_pk_mul_f32 v[28:29], v[6:7], v[28:29]
	v_cvt_pk_bf16_f32 v26, v26, v27
	v_cvt_pk_bf16_f32 v27, v28, v29
	global_store_dwordx4 v[44:45], v[24:27], off offset:512 sc0 sc1
	s_waitcnt vmcnt(9)
	s_nop 0
	v_lshlrev_b32_e32 v25, 16, v94
	v_lshlrev_b32_e32 v24, 16, v93
	s_waitcnt vmcnt(7)
	v_pk_mul_f32 v[26:27], v[68:69], v[24:25] op_sel:[0,1] op_sel_hi:[0,0]
	v_pk_fma_f32 v[28:29], v[66:67], v[24:25], v[26:27] neg_lo:[0,0,1] neg_hi:[0,0,1]
	v_pk_fma_f32 v[24:25], v[66:67], v[24:25], v[26:27] op_sel_hi:[0,1,1]
	v_cvt_pk_bf16_f32 v24, v28, v25
	global_store_dword v[40:41], v24, off sc0 sc1

; __device__ __forceinline__ unsigned cvtpk(float lo, float hi) { f32x2_t v = {lo, hi}; bf16x2_t b = __builtin_convertvector(v, bf16x2_t); return __builtin_bit_cast(unsigned, b); }
; __device__ __forceinline__ void mla_prep_phase(const bf16_t* projb, const float* gq, const float* gkv, const float* cs, bf16_t* cqn, bf16_t* ckvn, bf16_t* krope, int rows) {
;     ...
;             if (lane < 16) { u32x4 ob; ob.x = cvtpk(xb[0] * rkv * gB0[0], xb[1] * rkv * gB0[1]); ob.y = cvtpk(xb[2] * rkv * gB0[2], xb[3] * rkv * gB0[3]);
;                 ob.z = cvtpk(xb[4] * rkv * gB1[0], xb[5] * rkv * gB1[1]); ob.w = cvtpk(xb[6] * rkv * gB1[2], xb[7] * rkv * gB1[3]);
;                 *(u32x4*)(ckvn + (size_t)m * 256 + 8 * (16 + lane)) = ob;
;                 const float x1 = bf1(r1[r]), x2 = bf1(r2[r]);
;                 *(unsigned*)(krope + (size_t)m * 32 + 2 * lane) = cvtpk(x1 * cc[r] - x2 * sn[r], x1 * sn[r] + x2 * cc[r]); } }
.LBB0_240:
	v_pk_mul_f32 v[16:17], v[36:37], v[24:25] op_sel_hi:[0,1]
	v_pk_mul_f32 v[18:19], v[36:37], v[20:21] op_sel_hi:[0,1]
	v_pk_mul_f32 v[16:17], v[0:1], v[16:17]
	v_pk_mul_f32 v[18:19], v[2:3], v[18:19]
	v_cvt_pk_bf16_f32 v16, v16, v17
	v_cvt_pk_bf16_f32 v17, v18, v19
	v_pk_mul_f32 v[18:19], v[36:37], v[26:27] op_sel_hi:[0,1]
	v_pk_mul_f32 v[20:21], v[36:37], v[22:23] op_sel_hi:[0,1]
	v_pk_mul_f32 v[18:19], v[4:5], v[18:19]
	v_pk_mul_f32 v[20:21], v[6:7], v[20:21]
	v_cvt_pk_bf16_f32 v18, v18, v19
	v_cvt_pk_bf16_f32 v19, v20, v21
	global_store_dwordx4 v[44:45], v[16:19], off offset:1024 sc0 sc1
	s_waitcnt vmcnt(3)
	s_nop 0
	v_lshlrev_b32_e32 v17, 16, v92
	v_lshlrev_b32_e32 v16, 16, v49
	s_waitcnt vmcnt(1)
	v_pk_mul_f32 v[18:19], v[64:65], v[16:17] op_sel:[0,1] op_sel_hi:[0,0]
	v_pk_fma_f32 v[20:21], v[62:63], v[16:17], v[18:19] neg_lo:[0,0,1] neg_hi:[0,0,1]
	v_pk_fma_f32 v[16:17], v[62:63], v[16:17], v[18:19] op_sel_hi:[0,1,1]
	v_cvt_pk_bf16_f32 v16, v20, v17
	global_store_dword v[40:41], v16, off offset:64 sc0 sc1
	s_branch .LBB0_216

; __device__ __forceinline__ void dil_attn_unit(LAS unsigned char* lds, bf16_t* proj, float* lse, int unit, int Tc, bf16_t* ybuf) {
;     ...
;     mx = fmaxf(mx, __shfl_xor(mx, 32));
;     float ls = 0.f;
; #pragma unroll
;     for (int j = 0; j < 5; ++j)
; #pragma unroll
;         for (int rr = 0; rr < 16; ++rr) { const float e = __builtin_amdgcn_exp2f(p[j][rr] - mx); p[j][rr] = e; ls += e; }
.LBB0_261:
	v_xor_b32_e32 v0, 32, v199
	v_cmp_lt_i32_e32 vcc, v0, v211
	v_max_f32_e32 v1, v181, v181
	s_nop 0
	v_cndmask_b32_e32 v0, v199, v0, vcc
	v_lshlrev_b32_e32 v48, 2, v0
	ds_bpermute_b32 v0, v48, v181
	s_waitcnt lgkmcnt(0)
	v_max_f32_e32 v0, v0, v0
	v_max_f32_e32 v49, v1, v0
	v_sub_f32_e32 v0, v208, v49
	v_sub_f32_e32 v1, v209, v49
	v_exp_f32_e32 v0, v0
	v_exp_f32_e32 v1, v1
	v_sub_f32_e32 v2, v214, v49
	v_exp_f32_e32 v2, v2
	v_sub_f32_e32 v3, v215, v49
	v_exp_f32_e32 v3, v3
	v_add_f32_e32 v4, 0, v0
	v_add_f32_e32 v4, v1, v4
	v_add_f32_e32 v4, v2, v4
	v_add_f32_e32 v8, v3, v4
	v_sub_f32_e32 v4, v216, v49
	v_exp_f32_e32 v4, v4
	v_sub_f32_e32 v5, v217, v49
	v_exp_f32_e32 v5, v5
	v_sub_f32_e32 v6, v218, v49
	v_exp_f32_e32 v6, v6
	v_sub_f32_e32 v7, v219, v49
	v_exp_f32_e32 v7, v7
	v_add_f32_e32 v8, v4, v8
	v_add_f32_e32 v8, v5, v8
	v_add_f32_e32 v8, v6, v8
	v_add_f32_e32 v12, v7, v8
	v_sub_f32_e32 v8, v220, v49
	v_exp_f32_e32 v8, v8
	v_sub_f32_e32 v9, v221, v49
	v_exp_f32_e32 v9, v9
	v_sub_f32_e32 v10, v222, v49
	v_exp_f32_e32 v10, v10
	v_sub_f32_e32 v11, v223, v49
	v_exp_f32_e32 v11, v11
	v_add_f32_e32 v12, v8, v12
	v_add_f32_e32 v12, v9, v12
	v_add_f32_e32 v12, v10, v12
	v_add_f32_e32 v16, v11, v12
	v_sub_f32_e32 v12, v224, v49
	v_exp_f32_e32 v12, v12
	v_sub_f32_e32 v13, v225, v49
	v_exp_f32_e32 v13, v13
	v_sub_f32_e32 v14, v226, v49
	v_exp_f32_e32 v14, v14
	v_sub_f32_e32 v15, v227, v49
	v_exp_f32_e32 v15, v15
	v_sub_f32_e32 v17, v130, v49
	v_add_f32_e32 v16, v12, v16
	v_exp_f32_e32 v30, v17
	v_sub_f32_e32 v17, v131, v49
	v_add_f32_e32 v16, v13, v16
	v_exp_f32_e32 v31, v17
	v_sub_f32_e32 v17, v132, v49
	v_add_f32_e32 v16, v14, v16
	v_exp_f32_e32 v46, v17
	v_sub_f32_e32 v17, v133, v49
	v_add_f32_e32 v16, v15, v16
	v_exp_f32_e32 v47, v17
	v_sub_f32_e32 v17, v134, v49
	v_add_f32_e32 v16, v30, v16
	v_exp_f32_e32 v64, v17
	v_sub_f32_e32 v17, v135, v49
	v_add_f32_e32 v16, v31, v16
	v_exp_f32_e32 v65, v17
	v_sub_f32_e32 v17, v136, v49
	v_add_f32_e32 v16, v46, v16
	v_exp_f32_e32 v66, v17
	v_sub_f32_e32 v17, v137, v49
	v_add_f32_e32 v16, v47, v16
	v_exp_f32_e32 v67, v17
	v_sub_f32_e32 v17, v138, v49
	v_add_f32_e32 v16, v64, v16
	v_exp_f32_e32 v68, v17
	v_sub_f32_e32 v17, v139, v49
	v_add_f32_e32 v16, v65, v16
	v_exp_f32_e32 v69, v17
	v_sub_f32_e32 v17, v140, v49
	v_add_f32_e32 v16, v66, v16
	v_exp_f32_e32 v70, v17
	v_sub_f32_e32 v17, v141, v49
	v_add_f32_e32 v16, v67, v16
	v_exp_f32_e32 v71, v17
	v_sub_f32_e32 v17, v142, v49
	v_add_f32_e32 v16, v68, v16
	v_exp_f32_e32 v72, v17
	v_sub_f32_e32 v17, v143, v49
	v_add_f32_e32 v16, v69, v16
	v_exp_f32_e32 v73, v17
	v_sub_f32_e32 v17, v144, v49
	v_add_f32_e32 v16, v70, v16
	v_exp_f32_e32 v74, v17
	v_sub_f32_e32 v17, v145, v49
	v_add_f32_e32 v16, v71, v16
	v_exp_f32_e32 v75, v17
	v_sub_f32_e32 v17, v146, v49
	v_add_f32_e32 v16, v72, v16
	v_exp_f32_e32 v76, v17
	v_sub_f32_e32 v17, v147, v49
	v_add_f32_e32 v16, v73, v16
	v_exp_f32_e32 v77, v17
	v_sub_f32_e32 v17, v148, v49
	v_add_f32_e32 v16, v74, v16
	v_exp_f32_e32 v78, v17
	v_sub_f32_e32 v17, v149, v49
	v_add_f32_e32 v16, v75, v16
	v_exp_f32_e32 v79, v17
	v_sub_f32_e32 v17, v150, v49
	v_add_f32_e32 v16, v76, v16
	v_exp_f32_e32 v143, v17
	v_sub_f32_e32 v17, v151, v49
	v_add_f32_e32 v16, v77, v16
	v_exp_f32_e32 v144, v17
	v_sub_f32_e32 v17, v152, v49
	v_add_f32_e32 v16, v78, v16
	v_exp_f32_e32 v145, v17
	v_sub_f32_e32 v17, v153, v49
	v_add_f32_e32 v16, v79, v16
	v_exp_f32_e32 v146, v17
	v_add_f32_e32 v16, v143, v16
	v_add_f32_e32 v16, v144, v16
	v_add_f32_e32 v16, v145, v16
	v_add_f32_e32 v20, v146, v16
	v_sub_f32_e32 v16, v154, v49
	v_exp_f32_e32 v16, v16
	v_sub_f32_e32 v17, v155, v49
	v_exp_f32_e32 v17, v17
	v_sub_f32_e32 v18, v160, v49
	v_exp_f32_e32 v18, v18
	v_sub_f32_e32 v19, v161, v49
	v_exp_f32_e32 v19, v19
	v_add_f32_e32 v20, v16, v20
	v_add_f32_e32 v20, v17, v20
	v_add_f32_e32 v20, v18, v20
	v_add_f32_e32 v24, v19, v20
	v_sub_f32_e32 v20, v162, v49
	v_exp_f32_e32 v20, v20
	v_sub_f32_e32 v21, v163, v49
	v_exp_f32_e32 v21, v21
	v_sub_f32_e32 v22, v164, v49
	v_exp_f32_e32 v22, v22
	v_sub_f32_e32 v23, v165, v49
	v_exp_f32_e32 v23, v23
	v_add_f32_e32 v24, v20, v24
	v_add_f32_e32 v24, v21, v24
	v_add_f32_e32 v24, v22, v24
	v_add_f32_e32 v28, v23, v24
	v_sub_f32_e32 v24, v166, v49
	v_exp_f32_e32 v24, v24
	v_sub_f32_e32 v25, v167, v49
	v_exp_f32_e32 v25, v25
	v_sub_f32_e32 v26, v168, v49
	v_exp_f32_e32 v26, v26
	v_sub_f32_e32 v27, v169, v49
	v_exp_f32_e32 v27, v27
	v_add_f32_e32 v28, v24, v28
	v_add_f32_e32 v28, v25, v28
	v_add_f32_e32 v28, v26, v28
	v_add_f32_e32 v34, v27, v28
	v_sub_f32_e32 v28, v170, v49
	v_exp_f32_e32 v28, v28
	v_sub_f32_e32 v29, v171, v49
	v_exp_f32_e32 v29, v29
	v_sub_f32_e32 v32, v172, v49
	v_exp_f32_e32 v32, v32
	v_sub_f32_e32 v33, v173, v49
	v_exp_f32_e32 v33, v33
	v_add_f32_e32 v34, v28, v34
	v_add_f32_e32 v34, v29, v34
	v_add_f32_e32 v34, v32, v34
	v_add_f32_e32 v38, v33, v34
	v_sub_f32_e32 v34, v174, v49
	v_exp_f32_e32 v34, v34
	v_sub_f32_e32 v35, v175, v49
	v_exp_f32_e32 v35, v35
	v_sub_f32_e32 v36, v182, v49
	v_exp_f32_e32 v36, v36
	v_sub_f32_e32 v37, v183, v49
	v_exp_f32_e32 v37, v37
	v_add_f32_e32 v38, v34, v38
	v_add_f32_e32 v38, v35, v38
	v_add_f32_e32 v38, v36, v38
	v_add_f32_e32 v42, v37, v38
	v_sub_f32_e32 v38, v184, v49
	v_exp_f32_e32 v38, v38
	v_sub_f32_e32 v39, v185, v49
	v_exp_f32_e32 v39, v39
	v_sub_f32_e32 v40, v186, v49
	v_exp_f32_e32 v40, v40
	v_sub_f32_e32 v41, v187, v49
	v_exp_f32_e32 v41, v41
	v_add_f32_e32 v42, v38, v42
	v_add_f32_e32 v42, v39, v42
	v_add_f32_e32 v42, v40, v42
	v_add_f32_e32 v50, v41, v42
	v_sub_f32_e32 v42, v228, v49
	v_exp_f32_e32 v42, v42
	v_sub_f32_e32 v43, v229, v49
	v_exp_f32_e32 v43, v43
	v_sub_f32_e32 v44, v230, v49
	v_exp_f32_e32 v44, v44
	v_sub_f32_e32 v45, v231, v49
	v_exp_f32_e32 v45, v45
	v_sub_f32_e32 v51, v178, v49
	v_add_f32_e32 v50, v42, v50
	v_exp_f32_e32 v52, v51
	v_sub_f32_e32 v51, v232, v49
	v_add_f32_e32 v50, v43, v50
	v_exp_f32_e32 v53, v51
	v_sub_f32_e32 v51, v233, v49
	v_add_f32_e32 v50, v44, v50
	v_exp_f32_e32 v54, v51
	v_sub_f32_e32 v51, v234, v49
	v_add_f32_e32 v50, v45, v50
	v_exp_f32_e32 v55, v51
	v_sub_f32_e32 v51, v235, v49
	v_add_f32_e32 v50, v52, v50
	v_exp_f32_e32 v56, v51
	v_sub_f32_e32 v51, v236, v49
	v_add_f32_e32 v50, v53, v50
	v_exp_f32_e32 v57, v51
	v_sub_f32_e32 v51, v237, v49
	v_add_f32_e32 v50, v54, v50
	v_exp_f32_e32 v58, v51
	v_sub_f32_e32 v51, v238, v49
	v_add_f32_e32 v50, v55, v50
	v_exp_f32_e32 v59, v51
	v_sub_f32_e32 v51, v239, v49
	v_add_f32_e32 v50, v56, v50
	v_exp_f32_e32 v60, v51
	v_sub_f32_e32 v51, v240, v49
	v_add_f32_e32 v50, v57, v50
	v_exp_f32_e32 v61, v51
	v_sub_f32_e32 v51, v241, v49
	v_add_f32_e32 v50, v58, v50
	v_exp_f32_e32 v62, v51
	v_sub_f32_e32 v51, v128, v49
	v_add_f32_e32 v50, v59, v50
	v_exp_f32_e32 v63, v51
	v_add_f32_e32 v50, v60, v50
	v_add_f32_e32 v50, v61, v50
	v_add_f32_e32 v50, v62, v50
	v_add_f32_e32 v50, v63, v50
	ds_bpermute_b32 v48, v48, v50
	v_and_b32_e32 v141, 63, v189
	v_cmp_gt_u32_e32 vcc, 32, v141
	s_and_b64 s[36:37], s[90:91], vcc
	s_waitcnt lgkmcnt(0)
; __device__ __forceinline__ void dil_attn_unit(LAS unsigned char* lds, bf16_t* proj, float* lse, int unit, int Tc, bf16_t* ybuf) {
;     ...
;     ls += __shfl_xor(ls, 32);
;     const float inv = 1.0f / ls;
;     const float lse2 = mx + __builtin_amdgcn_logf(ls);
;     if (hi == 0 && !ybuf) lse[(rowbase + ((size_t)uq << dsh)) * 24 + g * 8 + h] = lse2;
	v_add_f32_e32 v48, v50, v48
	v_log_f32_e32 v50, v48
	s_nop 0
	v_add_f32_e32 v140, v49, v50
	s_and_saveexec_b64 s[0:1], s[36:37]
	s_cbranch_execz .LBB0_263
	s_add_u32 s36, s98, s76
	s_addc_u32 s37, s99, 0
	v_lshlrev_b64 v[50:51], s52, v[158:159]
	v_lshl_add_u64 v[50:51], s[36:37], 0, v[50:51]
	v_readlane_b32 s36, v254, 11
	v_readlane_b32 s37, v254, 12
	s_lshl_b32 s76, s53, 2
	s_nop 0
	v_mov_b64_e32 v[128:129], s[36:37]
	v_mad_u64_u32 v[128:129], s[36:37], v50, s66, v[128:129]
	v_mad_i32_i24 v129, v51, s66, v129
	v_lshl_add_u64 v[50:51], v[128:129], 0, s[76:77]
	s_lshl_b32 s76, s34, 2
	v_lshl_add_u64 v[50:51], v[50:51], 0, s[76:77]
	global_store_dword v[50:51], v140, off sc0 sc1
